# v77 + ssm_prep prologue: b_re/b_im (16) and c_re/c_im (4) loads pre-issued, h-loop unrolled on preloaded registers
# speedup vs baseline: 1.0200x; 1.0056x over previous
.LBB0_65:
	global_load_dword v6, v[2:3], off nt
	v_lshl_add_u64 v[2:3], v[2:3], 0, s[12:13]
	v_lshl_add_u64 v[4:5], v[2:3], 0, s[12:13]
	global_load_dword v7, v[2:3], off nt
	global_load_dword v8, v[4:5], off nt
	v_lshl_add_u64 v[2:3], v[4:5], 0, s[12:13]
	v_lshl_add_u64 v[4:5], v[2:3], 0, s[12:13]
	global_load_dword v9, v[2:3], off nt
	global_load_dword v10, v[4:5], off nt
	v_lshl_add_u64 v[2:3], v[4:5], 0, s[12:13]
	v_lshl_add_u64 v[4:5], v[2:3], 0, s[12:13]
	global_load_dword v11, v[2:3], off nt
	global_load_dword v12, v[4:5], off nt
	v_lshl_add_u64 v[2:3], v[4:5], 0, s[12:13]
	v_lshl_add_u64 v[4:5], v[2:3], 0, s[12:13]
	global_load_dword v13, v[2:3], off nt
	global_load_dword v14, v[4:5], off nt
	v_lshl_add_u64 v[2:3], v[4:5], 0, s[12:13]
	v_lshl_add_u64 v[4:5], v[2:3], 0, s[12:13]
	global_load_dword v15, v[2:3], off nt
	global_load_dword v16, v[4:5], off nt
	v_lshl_add_u64 v[2:3], v[4:5], 0, s[12:13]
	global_load_dword v4, v[2:3], off nt
	v_lshl_add_u64 v[2:3], v[2:3], 0, s[12:13]
	global_load_dword v5, v[2:3], off nt
	v_lshl_add_u64 v[2:3], v[2:3], 0, s[12:13]
	global_load_dword v17, v[2:3], off nt
	v_lshl_add_u64 v[2:3], v[2:3], 0, s[12:13]
	global_load_dword v18, v[2:3], off nt
	v_lshl_add_u64 v[2:3], v[2:3], 0, s[12:13]
	global_load_dword v19, v[2:3], off nt
	v_or_b32_e32 v20, s9, v87
	s_movk_i32 s19, 0x104
	v_mad_u32_u24 v20, v20, s19, v88
	v_lshl_add_u64 v[2:3], v[2:3], 0, s[12:13]
	global_load_dword v152, v[2:3], off nt
	v_lshl_add_u64 v[2:3], v[2:3], 0, s[12:13]
	v_lshl_add_u64 v[40:41], v[2:3], 0, s[12:13]
	global_load_dword v153, v[2:3], off nt
	global_load_dword v154, v[40:41], off nt
	v_lshl_add_u64 v[2:3], v[40:41], 0, s[12:13]
	v_lshl_add_u64 v[40:41], v[2:3], 0, s[12:13]
	global_load_dword v155, v[2:3], off nt
	global_load_dword v156, v[40:41], off nt
	v_lshl_add_u64 v[2:3], v[40:41], 0, s[12:13]
	v_lshl_add_u64 v[40:41], v[2:3], 0, s[12:13]
	global_load_dword v157, v[2:3], off nt
	global_load_dword v158, v[40:41], off nt
	v_lshl_add_u64 v[2:3], v[40:41], 0, s[12:13]
	v_lshl_add_u64 v[40:41], v[2:3], 0, s[12:13]
	global_load_dword v159, v[2:3], off nt
	global_load_dword v160, v[40:41], off nt
	v_lshl_add_u64 v[2:3], v[40:41], 0, s[12:13]
	v_lshl_add_u64 v[40:41], v[2:3], 0, s[12:13]
	global_load_dword v161, v[2:3], off nt
	global_load_dword v162, v[40:41], off nt
	v_lshl_add_u64 v[2:3], v[40:41], 0, s[12:13]
	global_load_dword v163, v[2:3], off nt
	v_lshl_add_u64 v[2:3], v[2:3], 0, s[12:13]
	global_load_dword v164, v[2:3], off nt
	v_lshl_add_u64 v[2:3], v[2:3], 0, s[12:13]
	global_load_dword v165, v[2:3], off nt
	v_lshl_add_u64 v[2:3], v[2:3], 0, s[12:13]
	global_load_dword v166, v[2:3], off nt
	v_lshl_add_u64 v[2:3], v[2:3], 0, s[12:13]
	global_load_dword v167, v[2:3], off nt
	s_movk_i32 s9, 0x80
	v_or_b32_e32 v168, s9, v87
	v_mad_u32_u24 v168, v168, s19, v88
	s_mov_b64 s[6:7], 0
	s_waitcnt vmcnt(31)
	ds_write_b32 v20, v6
	s_waitcnt vmcnt(30)
	ds_write_b32 v20, v7 offset:2080
	s_waitcnt vmcnt(29)
	ds_write_b32 v20, v8 offset:4160
	s_waitcnt vmcnt(28)
	ds_write_b32 v20, v9 offset:6240
	s_waitcnt vmcnt(27)
	ds_write_b32 v20, v10 offset:8320
	s_waitcnt vmcnt(26)
	ds_write_b32 v20, v11 offset:10400
	s_waitcnt vmcnt(25)
	ds_write_b32 v20, v12 offset:12480
	s_waitcnt vmcnt(24)
	ds_write_b32 v20, v13 offset:14560
	s_waitcnt vmcnt(23)
	ds_write_b32 v20, v14 offset:16640
	s_waitcnt vmcnt(22)
	ds_write_b32 v20, v15 offset:18720
	s_waitcnt vmcnt(21)
	ds_write_b32 v20, v16 offset:20800
	s_waitcnt vmcnt(20)
	ds_write_b32 v20, v4 offset:22880
	s_waitcnt vmcnt(19)
	ds_write_b32 v20, v5 offset:24960
	s_waitcnt vmcnt(18)
	ds_write_b32 v20, v17 offset:27040
	s_waitcnt vmcnt(17)
	ds_write_b32 v20, v18 offset:29120
	s_waitcnt vmcnt(16)
	ds_write_b32 v20, v19 offset:31200
	s_waitcnt vmcnt(15)
	ds_write_b32 v168, v152
	s_waitcnt vmcnt(14)
	ds_write_b32 v168, v153 offset:2080
	s_waitcnt vmcnt(13)
	ds_write_b32 v168, v154 offset:4160
	s_waitcnt vmcnt(12)
	ds_write_b32 v168, v155 offset:6240
	s_waitcnt vmcnt(11)
	ds_write_b32 v168, v156 offset:8320
	s_waitcnt vmcnt(10)
	ds_write_b32 v168, v157 offset:10400
	s_waitcnt vmcnt(9)
	ds_write_b32 v168, v158 offset:12480
	s_waitcnt vmcnt(8)
	ds_write_b32 v168, v159 offset:14560
	s_waitcnt vmcnt(7)
	ds_write_b32 v168, v160 offset:16640
	s_waitcnt vmcnt(6)
	ds_write_b32 v168, v161 offset:18720
	s_waitcnt vmcnt(5)
	ds_write_b32 v168, v162 offset:20800
	s_waitcnt vmcnt(4)
	ds_write_b32 v168, v163 offset:22880
	s_waitcnt vmcnt(3)
	ds_write_b32 v168, v164 offset:24960
	s_waitcnt vmcnt(2)
	ds_write_b32 v168, v165 offset:27040
	s_waitcnt vmcnt(1)
	ds_write_b32 v168, v166 offset:29120
	s_waitcnt vmcnt(0)
	ds_write_b32 v168, v167 offset:31200
	s_waitcnt lgkmcnt(0)
	s_barrier
	ds_read2_b32 v[6:7], v90 offset1:32
	v_add_u32_e32 v2, 0x400, v91
	ds_read2_b32 v[8:9], v2 offset0:4 offset1:36
	ds_read2_b32 v[10:11], v90 offset0:65 offset1:97
	ds_read2_b32 v[12:13], v2 offset0:69 offset1:101
	ds_read2_b32 v[14:15], v90 offset0:130 offset1:162
	ds_read2_b32 v[16:17], v90 offset0:195 offset1:227
	ds_read2_b32 v[18:19], v2 offset0:134 offset1:166
	ds_read2_b32 v[20:21], v2 offset0:199 offset1:231
	s_lshl_b32 s6, s8, 1
	ds_read2_b32 v[26:27], v93 offset1:65
	s_waitcnt lgkmcnt(6)
	v_cvt_pk_bf16_f32 v2, v6, v10
	v_or_b32_e32 v6, s18, v89
	v_mul_u32_u24_e32 v66, s27, v6
	v_add_u32_e32 v6, 0x400, v94
	ds_read2_b32 v[28:29], v93 offset0:130 offset1:195
	ds_read2_b32 v[30:31], v6 offset0:4 offset1:69
	ds_read2_b32 v[32:33], v6 offset0:134 offset1:199
	s_add_u32 s4, s4, s6
	s_addc_u32 s5, s5, 0
	v_mov_b32_e32 v79, v67
	v_lshl_add_u64 v[22:23], s[4:5], 0, v[78:79]
	v_or_b32_e32 v6, s18, v92
	s_waitcnt lgkmcnt(6)
	v_cvt_pk_bf16_f32 v3, v14, v16
	v_cvt_pk_bf16_f32 v4, v8, v12
	s_waitcnt lgkmcnt(4)
	v_cvt_pk_bf16_f32 v5, v18, v20
	v_lshl_add_u64 v[24:25], v[66:67], 1, v[22:23]
	v_mul_u32_u24_e32 v66, s27, v6
	global_store_dwordx4 v[24:25], v[2:5], off
	v_lshl_add_u64 v[24:25], v[66:67], 1, v[22:23]
	v_add_u32_e32 v14, 0x400, v98
	s_waitcnt lgkmcnt(3)
	v_cvt_pk_bf16_f32 v2, v26, v27
	s_waitcnt lgkmcnt(2)
	v_cvt_pk_bf16_f32 v3, v28, v29
	s_waitcnt lgkmcnt(1)
	v_cvt_pk_bf16_f32 v4, v30, v31
	s_waitcnt lgkmcnt(0)
	v_cvt_pk_bf16_f32 v5, v32, v33
	global_store_dwordx4 v[24:25], v[2:5], off
	v_or_b32_e32 v6, s18, v95
	v_mul_u32_u24_e32 v66, s27, v6
	v_cvt_pk_bf16_f32 v2, v7, v11
	v_cvt_pk_bf16_f32 v3, v15, v17
	v_cvt_pk_bf16_f32 v4, v9, v13
	ds_read2_b32 v[8:9], v97 offset1:65
	ds_read2_b32 v[10:11], v97 offset0:130 offset1:195
	ds_read2_b32 v[12:13], v14 offset0:4 offset1:69
	ds_read2_b32 v[14:15], v14 offset0:134 offset1:199
	v_cvt_pk_bf16_f32 v5, v19, v21
	v_lshl_add_u64 v[6:7], v[66:67], 1, v[22:23]
	global_store_dwordx4 v[6:7], v[2:5], off
	v_add_u32_e32 v6, s18, v96
	v_mul_hi_u32_u24_e32 v7, s27, v6
	v_mul_u32_u24_e32 v6, s27, v6
	s_waitcnt lgkmcnt(3)
	v_cvt_pk_bf16_f32 v2, v8, v9
	s_waitcnt lgkmcnt(2)
	v_cvt_pk_bf16_f32 v3, v10, v11
	s_waitcnt lgkmcnt(1)
	v_cvt_pk_bf16_f32 v4, v12, v13
	s_waitcnt lgkmcnt(0)
	v_cvt_pk_bf16_f32 v5, v14, v15
	v_lshl_add_u64 v[6:7], v[6:7], 1, v[22:23]
	global_store_dwordx4 v[6:7], v[2:5], off
	s_barrier

.LBB0_68:
	s_ashr_i32 s58, s26, 2
	s_and_b32 s12, s26, 3
	v_lshl_or_b32 v171, s58, 10, v1
	v_lshlrev_b32_e32 v171, 2, v171
	v_readlane_b32 s40, v254, 23
	v_readlane_b32 s41, v254, 24
	v_readlane_b32 s42, v254, 25
	v_readlane_b32 s43, v254, 26
	s_nop 4
	global_load_dword v204, v171, s[40:41] nt
	global_load_dword v205, v171, s[42:43] nt
	global_load_dword v206, v171, s[40:41] offset:2048 nt
	global_load_dword v207, v171, s[42:43] offset:2048 nt
	s_and_saveexec_b64 s[60:61], s[0:1]
	s_cbranch_execz .LBB0_83
	s_ashr_i32 s59, s58, 31
	v_readlane_b32 s16, v254, 5
	s_lshl_b64 s[4:5], s[58:59], 2
	v_readlane_b32 s28, v254, 17
	v_readlane_b32 s29, v254, 18
	s_add_u32 s4, s28, s4
	s_addc_u32 s5, s29, s5
	global_load_dword v8, v67, s[4:5] nt
	v_lshl_or_b32 v2, s58, 6, v1
	v_ashrrev_i32_e32 v3, 31, v2
	v_readlane_b32 s26, v254, 15
	v_readlane_b32 s27, v254, 16
	v_lshlrev_b64 v[6:7], 2, v[2:3]
	v_readlane_b32 s24, v254, 13
	v_lshl_add_u64 v[4:5], s[26:27], 0, v[6:7]
	global_load_dword v4, v[4:5], off nt
	v_readlane_b32 s25, v254, 14
	s_brev_b32 s4, 18
	v_readlane_b32 s17, v254, 6
	v_lshl_add_u64 v[6:7], s[24:25], 0, v[6:7]
	global_load_dword v6, v[6:7], off nt
	v_lshlrev_b32_e32 v170, 6, v2
	v_readlane_b32 s36, v254, 21
	v_readlane_b32 s37, v254, 22
	v_readlane_b32 s38, v254, 19
	v_readlane_b32 s39, v254, 20
	s_nop 4
	global_load_dwordx2 v[172:173], v170, s[36:37]
	global_load_dwordx2 v[188:189], v170, s[38:39]
	global_load_dwordx2 v[174:175], v170, s[36:37] offset:8
	global_load_dwordx2 v[190:191], v170, s[38:39] offset:8
	global_load_dwordx2 v[176:177], v170, s[36:37] offset:16
	global_load_dwordx2 v[192:193], v170, s[38:39] offset:16
	global_load_dwordx2 v[178:179], v170, s[36:37] offset:24
	global_load_dwordx2 v[194:195], v170, s[38:39] offset:24
	global_load_dwordx2 v[180:181], v170, s[36:37] offset:32
	global_load_dwordx2 v[196:197], v170, s[38:39] offset:32
	global_load_dwordx2 v[182:183], v170, s[36:37] offset:40
	global_load_dwordx2 v[198:199], v170, s[38:39] offset:40
	global_load_dwordx2 v[184:185], v170, s[36:37] offset:48
	global_load_dwordx2 v[200:201], v170, s[38:39] offset:48
	global_load_dwordx2 v[186:187], v170, s[36:37] offset:56
	global_load_dwordx2 v[202:203], v170, s[38:39] offset:56
	v_readlane_b32 s18, v254, 7
	v_readlane_b32 s19, v254, 8
	v_readlane_b32 s20, v254, 9
	v_readlane_b32 s21, v254, 10
	v_readlane_b32 s22, v254, 11
	v_readlane_b32 s23, v254, 12
	v_readlane_b32 s30, v254, 19
	v_readlane_b32 s31, v254, 20
	s_waitcnt vmcnt(18)
	v_mul_f32_e32 v5, 0x3fb8aa3b, v8
	v_fma_f32 v7, v8, s91, -v5
	v_rndne_f32_e32 v9, v5
	v_fmac_f32_e32 v7, 0x32a5705f, v8
	v_sub_f32_e32 v5, v5, v9
	v_add_f32_e32 v5, v5, v7
	v_cvt_i32_f32_e32 v9, v9
	v_exp_f32_e32 v5, v5
	v_cmp_ngt_f32_e32 vcc, s82, v8
	v_ldexp_f32 v5, v5, v9
	s_nop 0
	v_cndmask_b32_e32 v5, 0, v5, vcc
	v_cmp_nlt_f32_e32 vcc, s55, v8
	s_nop 1
	v_cndmask_b32_e32 v8, v118, v5, vcc
	s_waitcnt vmcnt(17)
	v_mul_f32_e32 v5, v8, v4
	v_and_b32_e32 v7, 0x7fffffff, v5
	v_lshrrev_b32_e32 v9, 23, v7
	v_and_b32_e32 v10, 0x7fffff, v7
	v_cmp_nlt_f32_e64 s[62:63], |v5|, s4
	v_add_u32_e32 v12, 0xffffff88, v9
	v_or_b32_e32 v11, 0x800000, v10
	s_and_saveexec_b64 s[4:5], s[62:63]
	s_xor_b64 s[26:27], exec, s[4:5]
	s_cbranch_execz .LBB0_71
	s_mov_b32 s8, 0xfe5163ab
	v_mad_u64_u32 v[14:15], s[8:9], v11, s8, 0
	v_mov_b32_e32 v66, v15
	s_mov_b32 s8, 0x3c439041
	v_mad_u64_u32 v[16:17], s[8:9], v11, s8, v[66:67]
	v_mov_b32_e32 v66, v17
	v_mad_u64_u32 v[18:19], s[8:9], v11, s83, v[66:67]
	v_cmp_lt_u32_e32 vcc, 63, v12
	v_mov_b32_e32 v66, v19
	v_mad_u64_u32 v[20:21], s[8:9], v11, s84, v[66:67]
	v_cndmask_b32_e32 v9, 0, v119, vcc
	v_add_u32_e32 v9, v9, v12
	v_mov_b32_e32 v66, v21
	v_cmp_lt_u32_e64 s[4:5], 31, v9
	v_mad_u64_u32 v[22:23], s[8:9], v11, s85, v[66:67]
	s_nop 0
	v_cndmask_b32_e64 v10, 0, v120, s[4:5]
	v_mov_b32_e32 v66, v23
	v_add_u32_e32 v9, v10, v9
	v_mad_u64_u32 v[24:25], s[8:9], v11, s86, v[66:67]
	v_cmp_lt_u32_e64 s[6:7], 31, v9
	v_mov_b32_e32 v66, v25
	v_mad_u64_u32 v[26:27], s[8:9], v11, s87, v[66:67]
	v_cndmask_b32_e64 v10, 0, v120, s[6:7]
	v_add_u32_e32 v9, v10, v9
	v_cndmask_b32_e32 v10, v24, v20, vcc
	v_cndmask_b32_e32 v13, v26, v22, vcc
	v_cndmask_b32_e32 v17, v27, v24, vcc
	v_cndmask_b32_e64 v15, v13, v10, s[4:5]
	v_cndmask_b32_e64 v13, v17, v13, s[4:5]
	v_cndmask_b32_e32 v17, v22, v18, vcc
	v_cndmask_b32_e64 v10, v10, v17, s[4:5]
	v_cndmask_b32_e64 v13, v13, v15, s[6:7]
	v_cndmask_b32_e64 v15, v15, v10, s[6:7]
	v_sub_u32_e32 v19, 32, v9
	v_alignbit_b32 v21, v13, v15, v19
	v_cmp_eq_u32_e64 s[8:9], 0, v9
	v_cndmask_b32_e32 v14, v18, v14, vcc
	s_nop 0
	v_cndmask_b32_e64 v9, v21, v13, s[8:9]
	v_cndmask_b32_e32 v13, v20, v16, vcc
	v_cndmask_b32_e64 v16, v17, v13, s[4:5]
	v_cndmask_b32_e64 v10, v10, v16, s[6:7]
	v_alignbit_b32 v17, v15, v10, v19
	v_cndmask_b32_e64 v13, v13, v14, s[4:5]
	v_cndmask_b32_e64 v15, v17, v15, s[8:9]
	v_bfe_u32 v21, v9, 29, 1
	v_cndmask_b32_e64 v13, v16, v13, s[6:7]
	v_alignbit_b32 v17, v9, v15, 30
	v_sub_u32_e32 v22, 0, v21
	v_alignbit_b32 v14, v10, v13, v19
	v_xor_b32_e32 v17, v17, v22
	v_cndmask_b32_e64 v10, v14, v10, s[8:9]
	v_alignbit_b32 v14, v15, v10, 30
	v_ffbh_u32_e32 v15, v17
	v_min_u32_e32 v15, 32, v15
	v_alignbit_b32 v10, v10, v13, 30
	v_xor_b32_e32 v14, v14, v22
	v_sub_u32_e32 v16, 31, v15
	v_xor_b32_e32 v10, v10, v22
	v_alignbit_b32 v17, v17, v14, v16
	v_alignbit_b32 v10, v14, v10, v16
	v_alignbit_b32 v13, v17, v10, 9
	v_ffbh_u32_e32 v14, v13
	v_min_u32_e32 v14, 32, v14
	v_lshrrev_b32_e32 v20, 29, v9
	v_not_b32_e32 v16, v14
	v_alignbit_b32 v10, v13, v10, v16
	v_lshlrev_b32_e32 v13, 31, v20
	v_or_b32_e32 v16, 0x33000000, v13
	v_add_lshl_u32 v14, v14, v15, 23
	v_lshrrev_b32_e32 v10, 9, v10
	v_sub_u32_e32 v14, v16, v14
	v_or_b32_e32 v13, 0.5, v13
	v_lshlrev_b32_e32 v15, 23, v15
	v_or_b32_e32 v10, v14, v10
	v_lshrrev_b32_e32 v14, 9, v17
	v_sub_u32_e32 v13, v13, v15
	v_or_b32_e32 v13, v14, v13
	v_mul_f32_e32 v14, 0x3fc90fda, v13
	v_fma_f32 v15, v13, s88, -v14
	v_fmac_f32_e32 v15, 0x33a22168, v13
	v_fmac_f32_e32 v15, 0x3fc90fda, v10
	v_lshrrev_b32_e32 v9, 30, v9
	v_add_f32_e32 v10, v14, v15
	v_add_u32_e32 v9, v21, v9

.LBB0_77:
	s_or_b64 exec, exec, s[4:5]
	s_waitcnt vmcnt(16)
	v_mul_f32_e32 v8, v8, v6
	v_mul_f32_e32 v11, 0x3fb8aa3b, v8
	v_fma_f32 v12, v8, s91, -v11
	v_rndne_f32_e32 v15, v11
	v_fmac_f32_e32 v12, 0x32a5705f, v8
	v_sub_f32_e32 v11, v11, v15
	v_add_f32_e32 v11, v11, v12
	v_cvt_i32_f32_e32 v12, v15
	v_exp_f32_e32 v11, v11
	v_cmp_ngt_f32_e32 vcc, s82, v8
	s_brev_b32 s4, 1
	v_readlane_b32 s16, v254, 21
	v_ldexp_f32 v11, v11, v12
	v_cndmask_b32_e32 v11, 0, v11, vcc
	v_cmp_nlt_f32_e32 vcc, s55, v8
	v_mul_f32_e32 v8, v10, v10
	v_fmamk_f32 v12, v8, 0xb94c1982, v114
	v_fmaak_f32 v12, v8, v12, 0xbe2aaa9d
	v_mul_f32_e32 v12, v8, v12
	v_fmac_f32_e32 v10, v10, v12
	v_fmamk_f32 v12, v8, 0x37d75334, v115
	v_fmaak_f32 v12, v8, v12, 0x3d2aabf7
	v_fmaak_f32 v12, v8, v12, 0xbf000004
	v_fma_f32 v8, v8, v12, 1.0
	v_and_b32_e32 v12, 1, v9
	v_cndmask_b32_e32 v11, v118, v11, vcc
	v_cmp_eq_u32_e32 vcc, 0, v12
	v_lshlrev_b32_e32 v9, 30, v9
	v_readlane_b32 s17, v254, 22
	v_cndmask_b32_e64 v8, -v10, v8, vcc
	v_mul_f32_e32 v10, v14, v14
	v_fmamk_f32 v12, v10, 0xb94c1982, v114
	v_fmaak_f32 v12, v10, v12, 0xbe2aaa9d
	v_mul_f32_e32 v12, v10, v12
	v_fmac_f32_e32 v14, v14, v12
	v_fmamk_f32 v12, v10, 0x37d75334, v115
	v_fmaak_f32 v12, v10, v12, 0x3d2aabf7
	v_fmaak_f32 v12, v10, v12, 0xbf000004
	v_bitop3_b32 v8, v9, v8, s4 bitop3:0x6c
	s_movk_i32 s4, 0x1f8
	v_fma_f32 v10, v10, v12, 1.0
	v_and_b32_e32 v12, 1, v13
	v_cmp_class_f32_e64 vcc, v5, s4
	v_cmp_eq_u32_e64 s[4:5], 0, v12
	v_lshlrev_b32_e32 v12, 30, v13
	v_and_b32_e32 v12, 0x80000000, v12
	v_xor_b32_e32 v5, v7, v5
	v_cndmask_b32_e64 v10, v10, v14, s[4:5]
	v_xor_b32_e32 v5, v5, v12
	v_xor_b32_e32 v5, v5, v10
	v_cndmask_b32_e32 v9, v121, v8, vcc
	v_cndmask_b32_e32 v5, v121, v5, vcc
	v_mul_f32_e32 v8, v11, v9
	v_mul_f32_e32 v10, v11, v5
	v_fma_f32 v12, v11, v9, -1.0
	v_mov_b32_e32 v11, v6
	v_mov_b32_e32 v13, v4
	v_pk_mul_f32 v[14:15], v[6:7], v[10:11] op_sel_hi:[0,1]
	v_pk_mul_f32 v[16:17], v[4:5], v[12:13] op_sel_hi:[0,1]
	v_sub_f32_e32 v11, v14, v16
	v_add_f32_e32 v15, v15, v17
	v_div_scale_f32 v5, s[4:5], v15, v15, v11
	v_rcp_f32_e32 v16, v5
	v_mov_b32_e32 v9, v10
	ds_write_b64 v99, v[8:9]
	v_lshlrev_b32_e32 v14, 4, v2
	v_fma_f32 v7, -v5, v16, 1.0
	v_fmac_f32_e32 v16, v7, v16
	v_div_scale_f32 v7, vcc, v11, v15, v11
	v_mul_f32_e32 v9, v7, v16
	v_fma_f32 v13, -v5, v9, v7
	v_fmac_f32_e32 v9, v13, v16
	v_fma_f32 v17, -v5, v9, v7
	v_mov_b32_e32 v7, v4
	v_mov_b32_e32 v13, v10
	v_pk_mul_f32 v[4:5], v[6:7], v[12:13]
	v_readlane_b32 s18, v254, 23
	v_add_f32_e32 v5, v4, v5
	v_div_scale_f32 v6, s[4:5], v15, v15, v5
	v_rcp_f32_e32 v7, v6
	v_div_fmas_f32 v4, v17, v16, v9
	v_div_fixup_f32 v4, v4, v15, v11
	v_readlane_b32 s19, v254, 24
	v_fma_f32 v9, -v6, v7, 1.0
	v_fmac_f32_e32 v7, v9, v7
	v_div_scale_f32 v9, vcc, v5, v15, v5
	v_mul_f32_e32 v11, v9, v7
	v_fma_f32 v12, -v6, v11, v9
	v_fmac_f32_e32 v11, v12, v7
	v_fma_f32 v6, -v6, v11, v9
	v_div_fmas_f32 v6, v6, v7, v11
	v_div_fixup_f32 v6, v6, v15, v5
	v_ashrrev_i32_e32 v15, 31, v14
	v_lshlrev_b64 v[14:15], 2, v[14:15]
	v_readlane_b32 s20, v254, 25
	v_readlane_b32 s21, v254, 26
	v_readlane_b32 s22, v254, 27
	v_readlane_b32 s23, v254, 28
	v_readlane_b32 s24, v254, 29
	v_readlane_b32 s25, v254, 30
	v_readlane_b32 s26, v254, 31
	v_readlane_b32 s27, v254, 32
	v_readlane_b32 s28, v254, 33
	v_readlane_b32 s29, v254, 34
	v_readlane_b32 s30, v254, 35
	v_readlane_b32 s31, v254, 36
	v_lshl_add_u64 v[12:13], s[16:17], 0, v[14:15]
	v_readlane_b32 s16, v254, 5
	v_readlane_b32 s30, v254, 19
	v_readlane_b32 s31, v254, 20
	v_mov_b32_e32 v7, v6
	v_mov_b32_e32 v5, v4
	v_lshl_add_u64 v[14:15], s[30:31], 0, v[14:15]
	s_mov_b64 s[4:5], 0
	v_mov_b32_e32 v9, v103
	v_readlane_b32 s17, v254, 6
	v_readlane_b32 s18, v254, 7
	v_readlane_b32 s19, v254, 8
	v_readlane_b32 s20, v254, 9
	v_readlane_b32 s21, v254, 10
	v_readlane_b32 s22, v254, 11
	v_readlane_b32 s23, v254, 12
	v_readlane_b32 s24, v254, 13
	v_readlane_b32 s25, v254, 14
	v_readlane_b32 s26, v254, 15
	v_readlane_b32 s27, v254, 16
	v_readlane_b32 s28, v254, 17
	v_readlane_b32 s29, v254, 18
.LBB0_78:
	s_waitcnt vmcnt(0)
	v_pk_mul_f32 v[20:21], v[4:5], v[172:173]
	v_pk_mul_f32 v[18:19], v[6:7], v[172:173]
	v_pk_fma_f32 v[20:21], v[6:7], v[188:189], v[20:21] neg_lo:[0,0,1] neg_hi:[0,0,1]
	v_pk_fma_f32 v[18:19], v[4:5], v[188:189], v[18:19]
	v_mov_b32_e32 v16, v20
	v_mov_b32_e32 v17, v18
	v_mov_b32_e32 v18, v21
	ds_write_b128 v9, v[16:19]
	v_add_u32_e32 v9, 16, v9
	v_pk_mul_f32 v[20:21], v[4:5], v[174:175]
	v_pk_mul_f32 v[18:19], v[6:7], v[174:175]
	v_pk_fma_f32 v[20:21], v[6:7], v[190:191], v[20:21] neg_lo:[0,0,1] neg_hi:[0,0,1]
	v_pk_fma_f32 v[18:19], v[4:5], v[190:191], v[18:19]
	v_mov_b32_e32 v16, v20
	v_mov_b32_e32 v17, v18
	v_mov_b32_e32 v18, v21
	ds_write_b128 v9, v[16:19]
	v_add_u32_e32 v9, 16, v9
	v_pk_mul_f32 v[20:21], v[4:5], v[176:177]
	v_pk_mul_f32 v[18:19], v[6:7], v[176:177]
	v_pk_fma_f32 v[20:21], v[6:7], v[192:193], v[20:21] neg_lo:[0,0,1] neg_hi:[0,0,1]
	v_pk_fma_f32 v[18:19], v[4:5], v[192:193], v[18:19]
	v_mov_b32_e32 v16, v20
	v_mov_b32_e32 v17, v18
	v_mov_b32_e32 v18, v21
	ds_write_b128 v9, v[16:19]
	v_add_u32_e32 v9, 16, v9
	v_pk_mul_f32 v[20:21], v[4:5], v[178:179]
	v_pk_mul_f32 v[18:19], v[6:7], v[178:179]
	v_pk_fma_f32 v[20:21], v[6:7], v[194:195], v[20:21] neg_lo:[0,0,1] neg_hi:[0,0,1]
	v_pk_fma_f32 v[18:19], v[4:5], v[194:195], v[18:19]
	v_mov_b32_e32 v16, v20
	v_mov_b32_e32 v17, v18
	v_mov_b32_e32 v18, v21
	ds_write_b128 v9, v[16:19]
	v_add_u32_e32 v9, 16, v9
	v_pk_mul_f32 v[20:21], v[4:5], v[180:181]
	v_pk_mul_f32 v[18:19], v[6:7], v[180:181]
	v_pk_fma_f32 v[20:21], v[6:7], v[196:197], v[20:21] neg_lo:[0,0,1] neg_hi:[0,0,1]
	v_pk_fma_f32 v[18:19], v[4:5], v[196:197], v[18:19]
	v_mov_b32_e32 v16, v20
	v_mov_b32_e32 v17, v18
	v_mov_b32_e32 v18, v21
	ds_write_b128 v9, v[16:19]
	v_add_u32_e32 v9, 16, v9
	v_pk_mul_f32 v[20:21], v[4:5], v[182:183]
	v_pk_mul_f32 v[18:19], v[6:7], v[182:183]
	v_pk_fma_f32 v[20:21], v[6:7], v[198:199], v[20:21] neg_lo:[0,0,1] neg_hi:[0,0,1]
	v_pk_fma_f32 v[18:19], v[4:5], v[198:199], v[18:19]
	v_mov_b32_e32 v16, v20
	v_mov_b32_e32 v17, v18
	v_mov_b32_e32 v18, v21
	ds_write_b128 v9, v[16:19]
	v_add_u32_e32 v9, 16, v9
	v_pk_mul_f32 v[20:21], v[4:5], v[184:185]
	v_pk_mul_f32 v[18:19], v[6:7], v[184:185]
	v_pk_fma_f32 v[20:21], v[6:7], v[200:201], v[20:21] neg_lo:[0,0,1] neg_hi:[0,0,1]
	v_pk_fma_f32 v[18:19], v[4:5], v[200:201], v[18:19]
	v_mov_b32_e32 v16, v20
	v_mov_b32_e32 v17, v18
	v_mov_b32_e32 v18, v21
	ds_write_b128 v9, v[16:19]
	v_add_u32_e32 v9, 16, v9
	v_pk_mul_f32 v[20:21], v[4:5], v[186:187]
	v_pk_mul_f32 v[18:19], v[6:7], v[186:187]
	v_pk_fma_f32 v[20:21], v[6:7], v[202:203], v[20:21] neg_lo:[0,0,1] neg_hi:[0,0,1]
	v_pk_fma_f32 v[18:19], v[4:5], v[202:203], v[18:19]
	v_mov_b32_e32 v16, v20
	v_mov_b32_e32 v17, v18
	v_mov_b32_e32 v18, v21
	ds_write_b128 v9, v[16:19]
	v_add_u32_e32 v9, 16, v9
	s_mov_b64 s[4:5], 64
	v_mov_b32_e32 v9, v8
	v_mov_b32_e32 v11, v10
	v_mov_b32_e32 v5, 0
	v_mov_b32_e32 v4, 1.0
	s_movk_i32 s4, 0xfef8

.LBB0_84:
	s_waitcnt vmcnt(0)
	ds_write_b64 v7, v[204:205]
	v_add_u32_e32 v7, 0x1000, v7
	ds_write_b64 v7, v[206:207]
	s_or_b64 exec, exec, s[4:5]
	s_lshl_b32 s8, s12, 2
	v_or_b32_e32 v2, s8, v100
	v_cmp_eq_u32_e32 vcc, v2, v228
	v_lshl_or_b32 v2, s58, 4, v2
	v_readlane_b32 s16, v254, 21
	v_ashrrev_i32_e32 v3, 31, v2
	v_readlane_b32 s22, v254, 27
	v_readlane_b32 s23, v254, 28
	v_lshl_add_u32 v4, s12, 11, v107
	s_mov_b32 s6, 0
	v_lshl_add_u64 v[2:3], v[2:3], 2, s[22:23]
	v_mov_b32_e32 v5, v109
	s_waitcnt lgkmcnt(0)
	s_barrier
	v_readlane_b32 s17, v254, 22
	v_readlane_b32 s18, v254, 23
	v_readlane_b32 s19, v254, 24
	v_readlane_b32 s20, v254, 25
	v_readlane_b32 s21, v254, 26
	v_readlane_b32 s24, v254, 29
	v_readlane_b32 s25, v254, 30
	v_readlane_b32 s26, v254, 31
	v_readlane_b32 s27, v254, 32
	v_readlane_b32 s28, v254, 33
	v_readlane_b32 s29, v254, 34
	v_readlane_b32 s30, v254, 35
	v_readlane_b32 s31, v254, 36
	s_branch .LBB0_87
